# up-projection epilogue (conv + tanh-GELU gate) hand-written: neighbour rows by DPP fused into v_fmac, folded GELU constants, 32-bit store offsets; 1527 -> 999 lines
# speedup vs baseline: 1.0122x; 1.0103x over previous
.LBB0_1151:
	v_readlane_b32 s51, v251, 4
	s_andn2_b64 vcc, exec, s[40:41]
	s_cbranch_vccnz .LBB0_1173
	s_nop 7
	s_nop 7
	v_lshl_or_b32 v176, s38, 7, v206
	v_lshlrev_b32_e32 v177, 2, v176
	v_add_u32_e32 v178, 0x5800, v177
	v_add_u32_e32 v179, 0xb000, v177
	global_load_dwordx4 v[102:105], v177, s[20:21]
	global_load_dwordx4 v[106:109], v177, s[20:21] offset:16
	global_load_dwordx4 v[110:113], v178, s[20:21]
	global_load_dwordx4 v[114:117], v178, s[20:21] offset:16
	global_load_dwordx4 v[118:121], v179, s[20:21]
	global_load_dwordx4 v[122:125], v179, s[20:21] offset:16
	global_load_dwordx4 v[126:129], v177, s[22:23]
	global_load_dwordx4 v[80:83], v177, s[22:23] offset:16
	v_lshlrev_b32_e32 v175, 1, v176
	s_lshl_b32 s40, s58, 8
	s_add_i32 s40, s40, s70
	s_movk_i32 s44, 0x2c00
	v_or_b32_e32 v174, s40, v192
	v_mov_b32_e32 v208, 0xbdd2d3e7
	s_mov_b32 s42, s31
	s_mov_b32 s43, s90
	s_ashr_i32 s41, s40, 4
	s_and_saveexec_b64 s[38:39], s[12:13]
	v_or_b32_e32 v176, s41, v192
	v_mad_u32_u24 v176, v176, s44, v175
	v_cvt_pk_bf16_f32 v188, v92, v93
	v_cvt_pk_bf16_f32 v189, v94, v95
	v_cvt_pk_bf16_f32 v190, v84, v85
	v_cvt_pk_bf16_f32 v191, v86, v87
	global_store_dwordx4 v176, v[188:191], s[62:63]
	s_and_b64 exec, exec, s[4:5]
	s_ashr_i32 s41, s40, 5
	s_mul_i32 s41, s41, s44
	v_add_u32_e32 v177, s41, v175
	v_cvt_pk_bf16_f32 v180, v98, v99
	v_cvt_pk_bf16_f32 v181, v100, v101
	v_cvt_pk_bf16_f32 v182, v88, v89
	v_cvt_pk_bf16_f32 v183, v90, v91
	global_store_dwordx4 v177, v[180:183], s[42:43]
	s_or_b64 exec, exec, s[38:39]
	s_ashr_i32 s41, s40, 4
	s_and_saveexec_b64 s[38:39], s[14:15]
	v_add_u32_e32 v178, s41, v205
	v_mad_u32_u24 v178, v178, s44, v175
	v_cvt_pk_bf16_f32 v184, v72, v73
	v_cvt_pk_bf16_f32 v185, v74, v75
	v_cvt_pk_bf16_f32 v186, v64, v65
	v_cvt_pk_bf16_f32 v187, v66, v67
	global_store_dwordx4 v178, v[184:187], s[62:63]
	s_and_b64 exec, exec, s[8:9]
	s_ashr_i32 s41, s40, 5
	s_or_b32 s41, s41, 1
	s_mul_i32 s41, s41, s44
	v_add_u32_e32 v179, s41, v175
	v_cvt_pk_bf16_f32 v188, v76, v77
	v_cvt_pk_bf16_f32 v189, v78, v79
	v_cvt_pk_bf16_f32 v190, v68, v69
	v_cvt_pk_bf16_f32 v191, v70, v71
	global_store_dwordx4 v179, v[188:191], s[42:43]
	s_or_b64 exec, exec, s[38:39]
	s_addk_i32 s40, 0x80
	s_ashr_i32 s41, s40, 4
	s_and_saveexec_b64 s[38:39], s[12:13]
	v_or_b32_e32 v176, s41, v192
	v_mad_u32_u24 v176, v176, s44, v175
	v_cvt_pk_bf16_f32 v188, v24, v25
	v_cvt_pk_bf16_f32 v189, v26, v27
	v_cvt_pk_bf16_f32 v190, v16, v17
	v_cvt_pk_bf16_f32 v191, v18, v19
	global_store_dwordx4 v176, v[188:191], s[62:63]
	s_and_b64 exec, exec, s[4:5]
	s_ashr_i32 s41, s40, 5
	s_mul_i32 s41, s41, s44
	v_add_u32_e32 v177, s41, v175
	v_cvt_pk_bf16_f32 v180, v28, v29
	v_cvt_pk_bf16_f32 v181, v30, v31
	v_cvt_pk_bf16_f32 v182, v20, v21
	v_cvt_pk_bf16_f32 v183, v22, v23
	global_store_dwordx4 v177, v[180:183], s[42:43]
	s_or_b64 exec, exec, s[38:39]
	s_ashr_i32 s41, s40, 4
	s_and_saveexec_b64 s[38:39], s[14:15]
	v_add_u32_e32 v178, s41, v205
	v_mad_u32_u24 v178, v178, s44, v175
	v_cvt_pk_bf16_f32 v184, v8, v9
	v_cvt_pk_bf16_f32 v185, v10, v11
	v_cvt_pk_bf16_f32 v186, v0, v1
	v_cvt_pk_bf16_f32 v187, v2, v3
	global_store_dwordx4 v178, v[184:187], s[62:63]
	s_and_b64 exec, exec, s[8:9]
	s_ashr_i32 s41, s40, 5
	s_or_b32 s41, s41, 1
	s_mul_i32 s41, s41, s44
	v_add_u32_e32 v179, s41, v175
	v_cvt_pk_bf16_f32 v188, v12, v13
	v_cvt_pk_bf16_f32 v189, v14, v15
	v_cvt_pk_bf16_f32 v190, v4, v5
	v_cvt_pk_bf16_f32 v191, v6, v7
	global_store_dwordx4 v179, v[188:191], s[42:43]
	s_or_b64 exec, exec, s[38:39]
	s_waitcnt vmcnt(8)
	v_cndmask_b32_e64 v176, v92, 0, s[8:9]
	v_cndmask_b32_e64 v177, v93, 0, s[8:9]
	v_cndmask_b32_e64 v178, v94, 0, s[8:9]
	v_cndmask_b32_e64 v179, v95, 0, s[8:9]
	v_cndmask_b32_e64 v180, v92, v150, s[4:5]
	v_cndmask_b32_e64 v181, v93, v151, s[4:5]
	v_cndmask_b32_e64 v182, v94, v152, s[4:5]
	v_cndmask_b32_e64 v183, v95, v153, s[4:5]
	v_fma_f32 v184, v110, v92, v126
	v_fma_f32 v185, v111, v93, v127
	v_fma_f32 v186, v112, v94, v128
	v_fma_f32 v187, v113, v95, v129
	v_fmac_f32_dpp v184, v176, v102 row_ror:1 row_mask:0xf bank_mask:0xf
	v_fmac_f32_dpp v185, v177, v103 row_ror:1 row_mask:0xf bank_mask:0xf
	v_fmac_f32_dpp v186, v178, v104 row_ror:1 row_mask:0xf bank_mask:0xf
	v_fmac_f32_dpp v187, v179, v105 row_ror:1 row_mask:0xf bank_mask:0xf
	v_fmac_f32_dpp v184, v180, v118 row_ror:15 row_mask:0xf bank_mask:0xf
	v_fmac_f32_dpp v185, v181, v119 row_ror:15 row_mask:0xf bank_mask:0xf
	v_fmac_f32_dpp v186, v182, v120 row_ror:15 row_mask:0xf bank_mask:0xf
	v_fmac_f32_dpp v187, v183, v121 row_ror:15 row_mask:0xf bank_mask:0xf
	v_mul_f32_e32 v176, v184, v184
	v_mul_f32_e32 v177, v185, v185
	v_mul_f32_e32 v178, v186, v186
	v_mul_f32_e32 v179, v187, v187
	v_fmaak_f32 v176, v176, v208, 0xc0135761
	v_fmaak_f32 v177, v177, v208, 0xc0135761
	v_fmaak_f32 v178, v178, v208, 0xc0135761
	v_fmaak_f32 v179, v179, v208, 0xc0135761
	v_mul_f32_e32 v176, v176, v184
	v_mul_f32_e32 v177, v177, v185
	v_mul_f32_e32 v178, v178, v186
	v_mul_f32_e32 v179, v179, v187
	v_exp_f32_e32 v176, v176
	v_exp_f32_e32 v177, v177
	v_exp_f32_e32 v178, v178
	v_exp_f32_e32 v179, v179
	v_add_f32_e32 v176, 1.0, v176
	v_add_f32_e32 v177, 1.0, v177
	v_add_f32_e32 v178, 1.0, v178
	v_add_f32_e32 v179, 1.0, v179
	v_rcp_f32_e32 v176, v176
	v_rcp_f32_e32 v177, v177
	v_rcp_f32_e32 v178, v178
	v_rcp_f32_e32 v179, v179
	v_mul_f32_e32 v184, v184, v176
	v_mul_f32_e32 v185, v185, v177
	v_mul_f32_e32 v186, v186, v178
	v_mul_f32_e32 v187, v187, v179
	v_mul_f32_e32 v184, v184, v98
	v_mul_f32_e32 v185, v185, v99
	v_mul_f32_e32 v186, v186, v100
	v_mul_f32_e32 v187, v187, v101
	v_cvt_pk_bf16_f32 v188, v184, v185
	v_cvt_pk_bf16_f32 v189, v186, v187
	v_cndmask_b32_e64 v176, v84, 0, s[8:9]
	v_cndmask_b32_e64 v177, v85, 0, s[8:9]
	v_cndmask_b32_e64 v178, v86, 0, s[8:9]
	v_cndmask_b32_e64 v179, v87, 0, s[8:9]
	v_cndmask_b32_e64 v180, v84, v142, s[4:5]
	v_cndmask_b32_e64 v181, v85, v143, s[4:5]
	v_cndmask_b32_e64 v182, v86, v144, s[4:5]
	v_cndmask_b32_e64 v183, v87, v145, s[4:5]
	v_fma_f32 v184, v114, v84, v80
	v_fma_f32 v185, v115, v85, v81
	v_fma_f32 v186, v116, v86, v82
	v_fma_f32 v187, v117, v87, v83
	v_fmac_f32_dpp v184, v176, v106 row_ror:1 row_mask:0xf bank_mask:0xf
	v_fmac_f32_dpp v185, v177, v107 row_ror:1 row_mask:0xf bank_mask:0xf
	v_fmac_f32_dpp v186, v178, v108 row_ror:1 row_mask:0xf bank_mask:0xf
	v_fmac_f32_dpp v187, v179, v109 row_ror:1 row_mask:0xf bank_mask:0xf
	v_fmac_f32_dpp v184, v180, v122 row_ror:15 row_mask:0xf bank_mask:0xf
	v_fmac_f32_dpp v185, v181, v123 row_ror:15 row_mask:0xf bank_mask:0xf
	v_fmac_f32_dpp v186, v182, v124 row_ror:15 row_mask:0xf bank_mask:0xf
	v_fmac_f32_dpp v187, v183, v125 row_ror:15 row_mask:0xf bank_mask:0xf
	v_mul_f32_e32 v176, v184, v184
	v_mul_f32_e32 v177, v185, v185
	v_mul_f32_e32 v178, v186, v186
	v_mul_f32_e32 v179, v187, v187
	v_fmaak_f32 v176, v176, v208, 0xc0135761
	v_fmaak_f32 v177, v177, v208, 0xc0135761
	v_fmaak_f32 v178, v178, v208, 0xc0135761
	v_fmaak_f32 v179, v179, v208, 0xc0135761
	v_mul_f32_e32 v176, v176, v184
	v_mul_f32_e32 v177, v177, v185
	v_mul_f32_e32 v178, v178, v186
	v_mul_f32_e32 v179, v179, v187
	v_exp_f32_e32 v176, v176
	v_exp_f32_e32 v177, v177
	v_exp_f32_e32 v178, v178
	v_exp_f32_e32 v179, v179
	v_add_f32_e32 v176, 1.0, v176
	v_add_f32_e32 v177, 1.0, v177
	v_add_f32_e32 v178, 1.0, v178
	v_add_f32_e32 v179, 1.0, v179
	v_rcp_f32_e32 v176, v176
	v_rcp_f32_e32 v177, v177
	v_rcp_f32_e32 v178, v178
	v_rcp_f32_e32 v179, v179
	v_mul_f32_e32 v184, v184, v176
	v_mul_f32_e32 v185, v185, v177
	v_mul_f32_e32 v186, v186, v178
	v_mul_f32_e32 v187, v187, v179
	v_mul_f32_e32 v184, v184, v88
	v_mul_f32_e32 v185, v185, v89
	v_mul_f32_e32 v186, v186, v90
	v_mul_f32_e32 v187, v187, v91
	v_cvt_pk_bf16_f32 v190, v184, v185
	v_cvt_pk_bf16_f32 v191, v186, v187
	v_mov_b32_e32 v176, v174
	v_mad_u32_u24 v176, v176, s44, v175
	s_and_saveexec_b64 s[38:39], s[6:7]
	global_store_dwordx4 v176, v[188:191], s[54:55]
	s_or_b64 exec, exec, s[38:39]
	v_cndmask_b32_e64 v176, v150, v92, s[8:9]
	v_cndmask_b32_e64 v177, v151, v93, s[8:9]
	v_cndmask_b32_e64 v178, v152, v94, s[8:9]
	v_cndmask_b32_e64 v179, v153, v95, s[8:9]
	v_cndmask_b32_e64 v180, v150, v134, s[4:5]
	v_cndmask_b32_e64 v181, v151, v135, s[4:5]
	v_cndmask_b32_e64 v182, v152, v136, s[4:5]
	v_cndmask_b32_e64 v183, v153, v137, s[4:5]
	v_fma_f32 v184, v110, v150, v126
	v_fma_f32 v185, v111, v151, v127
	v_fma_f32 v186, v112, v152, v128
	v_fma_f32 v187, v113, v153, v129
	v_fmac_f32_dpp v184, v176, v102 row_ror:1 row_mask:0xf bank_mask:0xf
	v_fmac_f32_dpp v185, v177, v103 row_ror:1 row_mask:0xf bank_mask:0xf
	v_fmac_f32_dpp v186, v178, v104 row_ror:1 row_mask:0xf bank_mask:0xf
	v_fmac_f32_dpp v187, v179, v105 row_ror:1 row_mask:0xf bank_mask:0xf
	v_fmac_f32_dpp v184, v180, v118 row_ror:15 row_mask:0xf bank_mask:0xf
	v_fmac_f32_dpp v185, v181, v119 row_ror:15 row_mask:0xf bank_mask:0xf
	v_fmac_f32_dpp v186, v182, v120 row_ror:15 row_mask:0xf bank_mask:0xf
	v_fmac_f32_dpp v187, v183, v121 row_ror:15 row_mask:0xf bank_mask:0xf
	v_mul_f32_e32 v176, v184, v184
	v_mul_f32_e32 v177, v185, v185
	v_mul_f32_e32 v178, v186, v186
	v_mul_f32_e32 v179, v187, v187
	v_fmaak_f32 v176, v176, v208, 0xc0135761
	v_fmaak_f32 v177, v177, v208, 0xc0135761
	v_fmaak_f32 v178, v178, v208, 0xc0135761
	v_fmaak_f32 v179, v179, v208, 0xc0135761
	v_mul_f32_e32 v176, v176, v184
	v_mul_f32_e32 v177, v177, v185
	v_mul_f32_e32 v178, v178, v186
	v_mul_f32_e32 v179, v179, v187
	v_exp_f32_e32 v176, v176
	v_exp_f32_e32 v177, v177
	v_exp_f32_e32 v178, v178
	v_exp_f32_e32 v179, v179
	v_add_f32_e32 v176, 1.0, v176
	v_add_f32_e32 v177, 1.0, v177
	v_add_f32_e32 v178, 1.0, v178
	v_add_f32_e32 v179, 1.0, v179
	v_rcp_f32_e32 v176, v176
	v_rcp_f32_e32 v177, v177
	v_rcp_f32_e32 v178, v178
	v_rcp_f32_e32 v179, v179
	v_mul_f32_e32 v184, v184, v176
	v_mul_f32_e32 v185, v185, v177
	v_mul_f32_e32 v186, v186, v178
	v_mul_f32_e32 v187, v187, v179
	v_mul_f32_e32 v184, v184, v158
	v_mul_f32_e32 v185, v185, v159
	v_mul_f32_e32 v186, v186, v160
	v_mul_f32_e32 v187, v187, v161
	v_cvt_pk_bf16_f32 v188, v184, v185
	v_cvt_pk_bf16_f32 v189, v186, v187
	v_cndmask_b32_e64 v176, v142, v84, s[8:9]
	v_cndmask_b32_e64 v177, v143, v85, s[8:9]
	v_cndmask_b32_e64 v178, v144, v86, s[8:9]
	v_cndmask_b32_e64 v179, v145, v87, s[8:9]
	v_cndmask_b32_e64 v180, v142, v130, s[4:5]
	v_cndmask_b32_e64 v181, v143, v131, s[4:5]
	v_cndmask_b32_e64 v182, v144, v132, s[4:5]
	v_cndmask_b32_e64 v183, v145, v133, s[4:5]
	v_fma_f32 v184, v114, v142, v80
	v_fma_f32 v185, v115, v143, v81
	v_fma_f32 v186, v116, v144, v82
	v_fma_f32 v187, v117, v145, v83
	v_fmac_f32_dpp v184, v176, v106 row_ror:1 row_mask:0xf bank_mask:0xf
	v_fmac_f32_dpp v185, v177, v107 row_ror:1 row_mask:0xf bank_mask:0xf
	v_fmac_f32_dpp v186, v178, v108 row_ror:1 row_mask:0xf bank_mask:0xf
	v_fmac_f32_dpp v187, v179, v109 row_ror:1 row_mask:0xf bank_mask:0xf
	v_fmac_f32_dpp v184, v180, v122 row_ror:15 row_mask:0xf bank_mask:0xf
	v_fmac_f32_dpp v185, v181, v123 row_ror:15 row_mask:0xf bank_mask:0xf
	v_fmac_f32_dpp v186, v182, v124 row_ror:15 row_mask:0xf bank_mask:0xf
	v_fmac_f32_dpp v187, v183, v125 row_ror:15 row_mask:0xf bank_mask:0xf
	v_mul_f32_e32 v176, v184, v184
	v_mul_f32_e32 v177, v185, v185
	v_mul_f32_e32 v178, v186, v186
	v_mul_f32_e32 v179, v187, v187
	v_fmaak_f32 v176, v176, v208, 0xc0135761
	v_fmaak_f32 v177, v177, v208, 0xc0135761
	v_fmaak_f32 v178, v178, v208, 0xc0135761
	v_fmaak_f32 v179, v179, v208, 0xc0135761
	v_mul_f32_e32 v176, v176, v184
	v_mul_f32_e32 v177, v177, v185
	v_mul_f32_e32 v178, v178, v186
	v_mul_f32_e32 v179, v179, v187
	v_exp_f32_e32 v176, v176
	v_exp_f32_e32 v177, v177
	v_exp_f32_e32 v178, v178
	v_exp_f32_e32 v179, v179
	v_add_f32_e32 v176, 1.0, v176
	v_add_f32_e32 v177, 1.0, v177
	v_add_f32_e32 v178, 1.0, v178
	v_add_f32_e32 v179, 1.0, v179
	v_rcp_f32_e32 v176, v176
	v_rcp_f32_e32 v177, v177
	v_rcp_f32_e32 v178, v178
	v_rcp_f32_e32 v179, v179
	v_mul_f32_e32 v184, v184, v176
	v_mul_f32_e32 v185, v185, v177
	v_mul_f32_e32 v186, v186, v178
	v_mul_f32_e32 v187, v187, v179
	v_mul_f32_e32 v184, v184, v154
	v_mul_f32_e32 v185, v185, v155
	v_mul_f32_e32 v186, v186, v156
	v_mul_f32_e32 v187, v187, v157
	v_cvt_pk_bf16_f32 v190, v184, v185
	v_cvt_pk_bf16_f32 v191, v186, v187
	v_or_b32_e32 v176, 16, v174
	v_mad_u32_u24 v176, v176, s44, v175
	global_store_dwordx4 v176, v[188:191], s[54:55]
	v_cndmask_b32_e64 v176, v134, v150, s[8:9]
	v_cndmask_b32_e64 v177, v135, v151, s[8:9]
	v_cndmask_b32_e64 v178, v136, v152, s[8:9]
	v_cndmask_b32_e64 v179, v137, v153, s[8:9]
	v_cndmask_b32_e64 v180, v134, v72, s[4:5]
	v_cndmask_b32_e64 v181, v135, v73, s[4:5]
	v_cndmask_b32_e64 v182, v136, v74, s[4:5]
	v_cndmask_b32_e64 v183, v137, v75, s[4:5]
	v_fma_f32 v184, v110, v134, v126
	v_fma_f32 v185, v111, v135, v127
	v_fma_f32 v186, v112, v136, v128
	v_fma_f32 v187, v113, v137, v129
	v_fmac_f32_dpp v184, v176, v102 row_ror:1 row_mask:0xf bank_mask:0xf
	v_fmac_f32_dpp v185, v177, v103 row_ror:1 row_mask:0xf bank_mask:0xf
	v_fmac_f32_dpp v186, v178, v104 row_ror:1 row_mask:0xf bank_mask:0xf
	v_fmac_f32_dpp v187, v179, v105 row_ror:1 row_mask:0xf bank_mask:0xf
	v_fmac_f32_dpp v184, v180, v118 row_ror:15 row_mask:0xf bank_mask:0xf
	v_fmac_f32_dpp v185, v181, v119 row_ror:15 row_mask:0xf bank_mask:0xf
	v_fmac_f32_dpp v186, v182, v120 row_ror:15 row_mask:0xf bank_mask:0xf
	v_fmac_f32_dpp v187, v183, v121 row_ror:15 row_mask:0xf bank_mask:0xf
	v_mul_f32_e32 v176, v184, v184
	v_mul_f32_e32 v177, v185, v185
	v_mul_f32_e32 v178, v186, v186
	v_mul_f32_e32 v179, v187, v187
	v_fmaak_f32 v176, v176, v208, 0xc0135761
	v_fmaak_f32 v177, v177, v208, 0xc0135761
	v_fmaak_f32 v178, v178, v208, 0xc0135761
	v_fmaak_f32 v179, v179, v208, 0xc0135761
	v_mul_f32_e32 v176, v176, v184
	v_mul_f32_e32 v177, v177, v185
	v_mul_f32_e32 v178, v178, v186
	v_mul_f32_e32 v179, v179, v187
	v_exp_f32_e32 v176, v176
	v_exp_f32_e32 v177, v177
	v_exp_f32_e32 v178, v178
	v_exp_f32_e32 v179, v179
	v_add_f32_e32 v176, 1.0, v176
	v_add_f32_e32 v177, 1.0, v177
	v_add_f32_e32 v178, 1.0, v178
	v_add_f32_e32 v179, 1.0, v179
	v_rcp_f32_e32 v176, v176
	v_rcp_f32_e32 v177, v177
	v_rcp_f32_e32 v178, v178
	v_rcp_f32_e32 v179, v179
	v_mul_f32_e32 v184, v184, v176
	v_mul_f32_e32 v185, v185, v177
	v_mul_f32_e32 v186, v186, v178
	v_mul_f32_e32 v187, v187, v179
	v_mul_f32_e32 v184, v184, v146
	v_mul_f32_e32 v185, v185, v147
	v_mul_f32_e32 v186, v186, v148
	v_mul_f32_e32 v187, v187, v149
	v_cvt_pk_bf16_f32 v188, v184, v185
	v_cvt_pk_bf16_f32 v189, v186, v187
	v_cndmask_b32_e64 v176, v130, v142, s[8:9]
	v_cndmask_b32_e64 v177, v131, v143, s[8:9]
	v_cndmask_b32_e64 v178, v132, v144, s[8:9]
	v_cndmask_b32_e64 v179, v133, v145, s[8:9]
	v_cndmask_b32_e64 v180, v130, v64, s[4:5]
	v_cndmask_b32_e64 v181, v131, v65, s[4:5]
	v_cndmask_b32_e64 v182, v132, v66, s[4:5]
	v_cndmask_b32_e64 v183, v133, v67, s[4:5]
	v_fma_f32 v184, v114, v130, v80
	v_fma_f32 v185, v115, v131, v81
	v_fma_f32 v186, v116, v132, v82
	v_fma_f32 v187, v117, v133, v83
	v_fmac_f32_dpp v184, v176, v106 row_ror:1 row_mask:0xf bank_mask:0xf
	v_fmac_f32_dpp v185, v177, v107 row_ror:1 row_mask:0xf bank_mask:0xf
	v_fmac_f32_dpp v186, v178, v108 row_ror:1 row_mask:0xf bank_mask:0xf
	v_fmac_f32_dpp v187, v179, v109 row_ror:1 row_mask:0xf bank_mask:0xf
	v_fmac_f32_dpp v184, v180, v122 row_ror:15 row_mask:0xf bank_mask:0xf
	v_fmac_f32_dpp v185, v181, v123 row_ror:15 row_mask:0xf bank_mask:0xf
	v_fmac_f32_dpp v186, v182, v124 row_ror:15 row_mask:0xf bank_mask:0xf
	v_fmac_f32_dpp v187, v183, v125 row_ror:15 row_mask:0xf bank_mask:0xf
	v_mul_f32_e32 v176, v184, v184
	v_mul_f32_e32 v177, v185, v185
	v_mul_f32_e32 v178, v186, v186
	v_mul_f32_e32 v179, v187, v187
	v_fmaak_f32 v176, v176, v208, 0xc0135761
	v_fmaak_f32 v177, v177, v208, 0xc0135761
	v_fmaak_f32 v178, v178, v208, 0xc0135761
	v_fmaak_f32 v179, v179, v208, 0xc0135761
	v_mul_f32_e32 v176, v176, v184
	v_mul_f32_e32 v177, v177, v185
	v_mul_f32_e32 v178, v178, v186
	v_mul_f32_e32 v179, v179, v187
	v_exp_f32_e32 v176, v176
	v_exp_f32_e32 v177, v177
	v_exp_f32_e32 v178, v178
	v_exp_f32_e32 v179, v179
	v_add_f32_e32 v176, 1.0, v176
	v_add_f32_e32 v177, 1.0, v177
	v_add_f32_e32 v178, 1.0, v178
	v_add_f32_e32 v179, 1.0, v179
	v_rcp_f32_e32 v176, v176
	v_rcp_f32_e32 v177, v177
	v_rcp_f32_e32 v178, v178
	v_rcp_f32_e32 v179, v179
	v_mul_f32_e32 v184, v184, v176
	v_mul_f32_e32 v185, v185, v177
	v_mul_f32_e32 v186, v186, v178
	v_mul_f32_e32 v187, v187, v179
	v_mul_f32_e32 v184, v184, v138
	v_mul_f32_e32 v185, v185, v139
	v_mul_f32_e32 v186, v186, v140
	v_mul_f32_e32 v187, v187, v141
	v_cvt_pk_bf16_f32 v190, v184, v185
	v_cvt_pk_bf16_f32 v191, v186, v187
	v_or_b32_e32 v176, 32, v174
	v_mad_u32_u24 v176, v176, s44, v175
	global_store_dwordx4 v176, v[188:191], s[54:55]
	v_cndmask_b32_e64 v176, v72, v134, s[8:9]
	v_cndmask_b32_e64 v177, v73, v135, s[8:9]
	v_cndmask_b32_e64 v178, v74, v136, s[8:9]
	v_cndmask_b32_e64 v179, v75, v137, s[8:9]
	v_cndmask_b32_e64 v180, v72, 0, s[4:5]
	v_cndmask_b32_e64 v181, v73, 0, s[4:5]
	v_cndmask_b32_e64 v182, v74, 0, s[4:5]
	v_cndmask_b32_e64 v183, v75, 0, s[4:5]
	v_fma_f32 v184, v110, v72, v126
	v_fma_f32 v185, v111, v73, v127
	v_fma_f32 v186, v112, v74, v128
	v_fma_f32 v187, v113, v75, v129
	v_fmac_f32_dpp v184, v176, v102 row_ror:1 row_mask:0xf bank_mask:0xf
	v_fmac_f32_dpp v185, v177, v103 row_ror:1 row_mask:0xf bank_mask:0xf
	v_fmac_f32_dpp v186, v178, v104 row_ror:1 row_mask:0xf bank_mask:0xf
	v_fmac_f32_dpp v187, v179, v105 row_ror:1 row_mask:0xf bank_mask:0xf
	v_fmac_f32_dpp v184, v180, v118 row_ror:15 row_mask:0xf bank_mask:0xf
	v_fmac_f32_dpp v185, v181, v119 row_ror:15 row_mask:0xf bank_mask:0xf
	v_fmac_f32_dpp v186, v182, v120 row_ror:15 row_mask:0xf bank_mask:0xf
	v_fmac_f32_dpp v187, v183, v121 row_ror:15 row_mask:0xf bank_mask:0xf
	v_mul_f32_e32 v176, v184, v184
	v_mul_f32_e32 v177, v185, v185
	v_mul_f32_e32 v178, v186, v186
	v_mul_f32_e32 v179, v187, v187
	v_fmaak_f32 v176, v176, v208, 0xc0135761
	v_fmaak_f32 v177, v177, v208, 0xc0135761
	v_fmaak_f32 v178, v178, v208, 0xc0135761
	v_fmaak_f32 v179, v179, v208, 0xc0135761
	v_mul_f32_e32 v176, v176, v184
	v_mul_f32_e32 v177, v177, v185
	v_mul_f32_e32 v178, v178, v186
	v_mul_f32_e32 v179, v179, v187
	v_exp_f32_e32 v176, v176
	v_exp_f32_e32 v177, v177
	v_exp_f32_e32 v178, v178
	v_exp_f32_e32 v179, v179
	v_add_f32_e32 v176, 1.0, v176
	v_add_f32_e32 v177, 1.0, v177
	v_add_f32_e32 v178, 1.0, v178
	v_add_f32_e32 v179, 1.0, v179
	v_rcp_f32_e32 v176, v176
	v_rcp_f32_e32 v177, v177
	v_rcp_f32_e32 v178, v178
	v_rcp_f32_e32 v179, v179
	v_mul_f32_e32 v184, v184, v176
	v_mul_f32_e32 v185, v185, v177
	v_mul_f32_e32 v186, v186, v178
	v_mul_f32_e32 v187, v187, v179
	v_mul_f32_e32 v184, v184, v76
	v_mul_f32_e32 v185, v185, v77
	v_mul_f32_e32 v186, v186, v78
	v_mul_f32_e32 v187, v187, v79
	v_cvt_pk_bf16_f32 v188, v184, v185
	v_cvt_pk_bf16_f32 v189, v186, v187
	v_cndmask_b32_e64 v176, v64, v130, s[8:9]
	v_cndmask_b32_e64 v177, v65, v131, s[8:9]
	v_cndmask_b32_e64 v178, v66, v132, s[8:9]
	v_cndmask_b32_e64 v179, v67, v133, s[8:9]
	v_cndmask_b32_e64 v180, v64, 0, s[4:5]
	v_cndmask_b32_e64 v181, v65, 0, s[4:5]
	v_cndmask_b32_e64 v182, v66, 0, s[4:5]
	v_cndmask_b32_e64 v183, v67, 0, s[4:5]
	v_fma_f32 v184, v114, v64, v80
	v_fma_f32 v185, v115, v65, v81
	v_fma_f32 v186, v116, v66, v82
	v_fma_f32 v187, v117, v67, v83
	v_fmac_f32_dpp v184, v176, v106 row_ror:1 row_mask:0xf bank_mask:0xf
	v_fmac_f32_dpp v185, v177, v107 row_ror:1 row_mask:0xf bank_mask:0xf
	v_fmac_f32_dpp v186, v178, v108 row_ror:1 row_mask:0xf bank_mask:0xf
	v_fmac_f32_dpp v187, v179, v109 row_ror:1 row_mask:0xf bank_mask:0xf
	v_fmac_f32_dpp v184, v180, v122 row_ror:15 row_mask:0xf bank_mask:0xf
	v_fmac_f32_dpp v185, v181, v123 row_ror:15 row_mask:0xf bank_mask:0xf
	v_fmac_f32_dpp v186, v182, v124 row_ror:15 row_mask:0xf bank_mask:0xf
	v_fmac_f32_dpp v187, v183, v125 row_ror:15 row_mask:0xf bank_mask:0xf
	v_mul_f32_e32 v176, v184, v184
	v_mul_f32_e32 v177, v185, v185
	v_mul_f32_e32 v178, v186, v186
	v_mul_f32_e32 v179, v187, v187
	v_fmaak_f32 v176, v176, v208, 0xc0135761
	v_fmaak_f32 v177, v177, v208, 0xc0135761
	v_fmaak_f32 v178, v178, v208, 0xc0135761
	v_fmaak_f32 v179, v179, v208, 0xc0135761
	v_mul_f32_e32 v176, v176, v184
	v_mul_f32_e32 v177, v177, v185
	v_mul_f32_e32 v178, v178, v186
	v_mul_f32_e32 v179, v179, v187
	v_exp_f32_e32 v176, v176
	v_exp_f32_e32 v177, v177
	v_exp_f32_e32 v178, v178
	v_exp_f32_e32 v179, v179
	v_add_f32_e32 v176, 1.0, v176
	v_add_f32_e32 v177, 1.0, v177
	v_add_f32_e32 v178, 1.0, v178
	v_add_f32_e32 v179, 1.0, v179
	v_rcp_f32_e32 v176, v176
	v_rcp_f32_e32 v177, v177
	v_rcp_f32_e32 v178, v178
	v_rcp_f32_e32 v179, v179
	v_mul_f32_e32 v184, v184, v176
	v_mul_f32_e32 v185, v185, v177
	v_mul_f32_e32 v186, v186, v178
	v_mul_f32_e32 v187, v187, v179
	v_mul_f32_e32 v184, v184, v68
	v_mul_f32_e32 v185, v185, v69
	v_mul_f32_e32 v186, v186, v70
	v_mul_f32_e32 v187, v187, v71
	v_cvt_pk_bf16_f32 v190, v184, v185
	v_cvt_pk_bf16_f32 v191, v186, v187
	v_or_b32_e32 v176, 48, v174
	v_mad_u32_u24 v176, v176, s44, v175
	s_and_saveexec_b64 s[38:39], s[10:11]
	global_store_dwordx4 v176, v[188:191], s[54:55]
	s_or_b64 exec, exec, s[38:39]
	v_cndmask_b32_e64 v176, v24, 0, s[8:9]
	v_cndmask_b32_e64 v177, v25, 0, s[8:9]
	v_cndmask_b32_e64 v178, v26, 0, s[8:9]
	v_cndmask_b32_e64 v179, v27, 0, s[8:9]
	v_cndmask_b32_e64 v180, v24, v52, s[4:5]
	v_cndmask_b32_e64 v181, v25, v53, s[4:5]
	v_cndmask_b32_e64 v182, v26, v54, s[4:5]
	v_cndmask_b32_e64 v183, v27, v55, s[4:5]
	v_fma_f32 v184, v110, v24, v126
	v_fma_f32 v185, v111, v25, v127
	v_fma_f32 v186, v112, v26, v128
	v_fma_f32 v187, v113, v27, v129
	v_fmac_f32_dpp v184, v176, v102 row_ror:1 row_mask:0xf bank_mask:0xf
	v_fmac_f32_dpp v185, v177, v103 row_ror:1 row_mask:0xf bank_mask:0xf
	v_fmac_f32_dpp v186, v178, v104 row_ror:1 row_mask:0xf bank_mask:0xf
	v_fmac_f32_dpp v187, v179, v105 row_ror:1 row_mask:0xf bank_mask:0xf
	v_fmac_f32_dpp v184, v180, v118 row_ror:15 row_mask:0xf bank_mask:0xf
	v_fmac_f32_dpp v185, v181, v119 row_ror:15 row_mask:0xf bank_mask:0xf
	v_fmac_f32_dpp v186, v182, v120 row_ror:15 row_mask:0xf bank_mask:0xf
	v_fmac_f32_dpp v187, v183, v121 row_ror:15 row_mask:0xf bank_mask:0xf
	v_mul_f32_e32 v176, v184, v184
	v_mul_f32_e32 v177, v185, v185
	v_mul_f32_e32 v178, v186, v186
	v_mul_f32_e32 v179, v187, v187
	v_fmaak_f32 v176, v176, v208, 0xc0135761
	v_fmaak_f32 v177, v177, v208, 0xc0135761
	v_fmaak_f32 v178, v178, v208, 0xc0135761
	v_fmaak_f32 v179, v179, v208, 0xc0135761
	v_mul_f32_e32 v176, v176, v184
	v_mul_f32_e32 v177, v177, v185
	v_mul_f32_e32 v178, v178, v186
	v_mul_f32_e32 v179, v179, v187
	v_exp_f32_e32 v176, v176
	v_exp_f32_e32 v177, v177
	v_exp_f32_e32 v178, v178
	v_exp_f32_e32 v179, v179
	v_add_f32_e32 v176, 1.0, v176
	v_add_f32_e32 v177, 1.0, v177
	v_add_f32_e32 v178, 1.0, v178
	v_add_f32_e32 v179, 1.0, v179
	v_rcp_f32_e32 v176, v176
	v_rcp_f32_e32 v177, v177
	v_rcp_f32_e32 v178, v178
	v_rcp_f32_e32 v179, v179
	v_mul_f32_e32 v184, v184, v176
	v_mul_f32_e32 v185, v185, v177
	v_mul_f32_e32 v186, v186, v178
	v_mul_f32_e32 v187, v187, v179
	v_mul_f32_e32 v184, v184, v28
	v_mul_f32_e32 v185, v185, v29
	v_mul_f32_e32 v186, v186, v30
	v_mul_f32_e32 v187, v187, v31
	v_cvt_pk_bf16_f32 v188, v184, v185
	v_cvt_pk_bf16_f32 v189, v186, v187
	v_cndmask_b32_e64 v176, v16, 0, s[8:9]
	v_cndmask_b32_e64 v177, v17, 0, s[8:9]
	v_cndmask_b32_e64 v178, v18, 0, s[8:9]
	v_cndmask_b32_e64 v179, v19, 0, s[8:9]
	v_cndmask_b32_e64 v180, v16, v44, s[4:5]
	v_cndmask_b32_e64 v181, v17, v45, s[4:5]
	v_cndmask_b32_e64 v182, v18, v46, s[4:5]
	v_cndmask_b32_e64 v183, v19, v47, s[4:5]
	v_fma_f32 v184, v114, v16, v80
	v_fma_f32 v185, v115, v17, v81
	v_fma_f32 v186, v116, v18, v82
	v_fma_f32 v187, v117, v19, v83
	v_fmac_f32_dpp v184, v176, v106 row_ror:1 row_mask:0xf bank_mask:0xf
	v_fmac_f32_dpp v185, v177, v107 row_ror:1 row_mask:0xf bank_mask:0xf
	v_fmac_f32_dpp v186, v178, v108 row_ror:1 row_mask:0xf bank_mask:0xf
	v_fmac_f32_dpp v187, v179, v109 row_ror:1 row_mask:0xf bank_mask:0xf
	v_fmac_f32_dpp v184, v180, v122 row_ror:15 row_mask:0xf bank_mask:0xf
	v_fmac_f32_dpp v185, v181, v123 row_ror:15 row_mask:0xf bank_mask:0xf
	v_fmac_f32_dpp v186, v182, v124 row_ror:15 row_mask:0xf bank_mask:0xf
	v_fmac_f32_dpp v187, v183, v125 row_ror:15 row_mask:0xf bank_mask:0xf
	v_mul_f32_e32 v176, v184, v184
	v_mul_f32_e32 v177, v185, v185
	v_mul_f32_e32 v178, v186, v186
	v_mul_f32_e32 v179, v187, v187
	v_fmaak_f32 v176, v176, v208, 0xc0135761
	v_fmaak_f32 v177, v177, v208, 0xc0135761
	v_fmaak_f32 v178, v178, v208, 0xc0135761
	v_fmaak_f32 v179, v179, v208, 0xc0135761
	v_mul_f32_e32 v176, v176, v184
	v_mul_f32_e32 v177, v177, v185
	v_mul_f32_e32 v178, v178, v186
	v_mul_f32_e32 v179, v179, v187
	v_exp_f32_e32 v176, v176
	v_exp_f32_e32 v177, v177
	v_exp_f32_e32 v178, v178
	v_exp_f32_e32 v179, v179
	v_add_f32_e32 v176, 1.0, v176
	v_add_f32_e32 v177, 1.0, v177
	v_add_f32_e32 v178, 1.0, v178
	v_add_f32_e32 v179, 1.0, v179
	v_rcp_f32_e32 v176, v176
	v_rcp_f32_e32 v177, v177
	v_rcp_f32_e32 v178, v178
	v_rcp_f32_e32 v179, v179
	v_mul_f32_e32 v184, v184, v176
	v_mul_f32_e32 v185, v185, v177
	v_mul_f32_e32 v186, v186, v178
	v_mul_f32_e32 v187, v187, v179
	v_mul_f32_e32 v184, v184, v20
	v_mul_f32_e32 v185, v185, v21
	v_mul_f32_e32 v186, v186, v22
	v_mul_f32_e32 v187, v187, v23
	v_cvt_pk_bf16_f32 v190, v184, v185
	v_cvt_pk_bf16_f32 v191, v186, v187
	v_or_b32_e32 v176, 0x80, v174
	v_mad_u32_u24 v176, v176, s44, v175
	s_and_saveexec_b64 s[38:39], s[6:7]
	global_store_dwordx4 v176, v[188:191], s[54:55]
	s_or_b64 exec, exec, s[38:39]
	v_cndmask_b32_e64 v176, v52, v24, s[8:9]
	v_cndmask_b32_e64 v177, v53, v25, s[8:9]
	v_cndmask_b32_e64 v178, v54, v26, s[8:9]
	v_cndmask_b32_e64 v179, v55, v27, s[8:9]
	v_cndmask_b32_e64 v180, v52, v36, s[4:5]
	v_cndmask_b32_e64 v181, v53, v37, s[4:5]
	v_cndmask_b32_e64 v182, v54, v38, s[4:5]
	v_cndmask_b32_e64 v183, v55, v39, s[4:5]
	v_fma_f32 v184, v110, v52, v126
	v_fma_f32 v185, v111, v53, v127
	v_fma_f32 v186, v112, v54, v128
	v_fma_f32 v187, v113, v55, v129
	v_fmac_f32_dpp v184, v176, v102 row_ror:1 row_mask:0xf bank_mask:0xf
	v_fmac_f32_dpp v185, v177, v103 row_ror:1 row_mask:0xf bank_mask:0xf
	v_fmac_f32_dpp v186, v178, v104 row_ror:1 row_mask:0xf bank_mask:0xf
	v_fmac_f32_dpp v187, v179, v105 row_ror:1 row_mask:0xf bank_mask:0xf
	v_fmac_f32_dpp v184, v180, v118 row_ror:15 row_mask:0xf bank_mask:0xf
	v_fmac_f32_dpp v185, v181, v119 row_ror:15 row_mask:0xf bank_mask:0xf
	v_fmac_f32_dpp v186, v182, v120 row_ror:15 row_mask:0xf bank_mask:0xf
	v_fmac_f32_dpp v187, v183, v121 row_ror:15 row_mask:0xf bank_mask:0xf
	v_mul_f32_e32 v176, v184, v184
	v_mul_f32_e32 v177, v185, v185
	v_mul_f32_e32 v178, v186, v186
	v_mul_f32_e32 v179, v187, v187
	v_fmaak_f32 v176, v176, v208, 0xc0135761
	v_fmaak_f32 v177, v177, v208, 0xc0135761
	v_fmaak_f32 v178, v178, v208, 0xc0135761
	v_fmaak_f32 v179, v179, v208, 0xc0135761
	v_mul_f32_e32 v176, v176, v184
	v_mul_f32_e32 v177, v177, v185
	v_mul_f32_e32 v178, v178, v186
	v_mul_f32_e32 v179, v179, v187
	v_exp_f32_e32 v176, v176
	v_exp_f32_e32 v177, v177
	v_exp_f32_e32 v178, v178
	v_exp_f32_e32 v179, v179
	v_add_f32_e32 v176, 1.0, v176
	v_add_f32_e32 v177, 1.0, v177
	v_add_f32_e32 v178, 1.0, v178
	v_add_f32_e32 v179, 1.0, v179
	v_rcp_f32_e32 v176, v176
	v_rcp_f32_e32 v177, v177
	v_rcp_f32_e32 v178, v178
	v_rcp_f32_e32 v179, v179
	v_mul_f32_e32 v184, v184, v176
	v_mul_f32_e32 v185, v185, v177
	v_mul_f32_e32 v186, v186, v178
	v_mul_f32_e32 v187, v187, v179
	v_mul_f32_e32 v184, v184, v60
	v_mul_f32_e32 v185, v185, v61
	v_mul_f32_e32 v186, v186, v62
	v_mul_f32_e32 v187, v187, v63
	v_cvt_pk_bf16_f32 v188, v184, v185
	v_cvt_pk_bf16_f32 v189, v186, v187
	v_cndmask_b32_e64 v176, v44, v16, s[8:9]
	v_cndmask_b32_e64 v177, v45, v17, s[8:9]
	v_cndmask_b32_e64 v178, v46, v18, s[8:9]
	v_cndmask_b32_e64 v179, v47, v19, s[8:9]
	v_cndmask_b32_e64 v180, v44, v32, s[4:5]
	v_cndmask_b32_e64 v181, v45, v33, s[4:5]
	v_cndmask_b32_e64 v182, v46, v34, s[4:5]
	v_cndmask_b32_e64 v183, v47, v35, s[4:5]
	v_fma_f32 v184, v114, v44, v80
	v_fma_f32 v185, v115, v45, v81
	v_fma_f32 v186, v116, v46, v82
	v_fma_f32 v187, v117, v47, v83
	v_fmac_f32_dpp v184, v176, v106 row_ror:1 row_mask:0xf bank_mask:0xf
	v_fmac_f32_dpp v185, v177, v107 row_ror:1 row_mask:0xf bank_mask:0xf
	v_fmac_f32_dpp v186, v178, v108 row_ror:1 row_mask:0xf bank_mask:0xf
	v_fmac_f32_dpp v187, v179, v109 row_ror:1 row_mask:0xf bank_mask:0xf
	v_fmac_f32_dpp v184, v180, v122 row_ror:15 row_mask:0xf bank_mask:0xf
	v_fmac_f32_dpp v185, v181, v123 row_ror:15 row_mask:0xf bank_mask:0xf
	v_fmac_f32_dpp v186, v182, v124 row_ror:15 row_mask:0xf bank_mask:0xf
	v_fmac_f32_dpp v187, v183, v125 row_ror:15 row_mask:0xf bank_mask:0xf
	v_mul_f32_e32 v176, v184, v184
	v_mul_f32_e32 v177, v185, v185
	v_mul_f32_e32 v178, v186, v186
	v_mul_f32_e32 v179, v187, v187
	v_fmaak_f32 v176, v176, v208, 0xc0135761
	v_fmaak_f32 v177, v177, v208, 0xc0135761
	v_fmaak_f32 v178, v178, v208, 0xc0135761
	v_fmaak_f32 v179, v179, v208, 0xc0135761
	v_mul_f32_e32 v176, v176, v184
	v_mul_f32_e32 v177, v177, v185
	v_mul_f32_e32 v178, v178, v186
	v_mul_f32_e32 v179, v179, v187
	v_exp_f32_e32 v176, v176
	v_exp_f32_e32 v177, v177
	v_exp_f32_e32 v178, v178
	v_exp_f32_e32 v179, v179
	v_add_f32_e32 v176, 1.0, v176
	v_add_f32_e32 v177, 1.0, v177
	v_add_f32_e32 v178, 1.0, v178
	v_add_f32_e32 v179, 1.0, v179
	v_rcp_f32_e32 v176, v176
	v_rcp_f32_e32 v177, v177
	v_rcp_f32_e32 v178, v178
	v_rcp_f32_e32 v179, v179
	v_mul_f32_e32 v184, v184, v176
	v_mul_f32_e32 v185, v185, v177
	v_mul_f32_e32 v186, v186, v178
	v_mul_f32_e32 v187, v187, v179
	v_mul_f32_e32 v184, v184, v56
	v_mul_f32_e32 v185, v185, v57
	v_mul_f32_e32 v186, v186, v58
	v_mul_f32_e32 v187, v187, v59
	v_cvt_pk_bf16_f32 v190, v184, v185
	v_cvt_pk_bf16_f32 v191, v186, v187
	v_or_b32_e32 v176, 0x90, v174
	v_mad_u32_u24 v176, v176, s44, v175
	global_store_dwordx4 v176, v[188:191], s[54:55]
	v_cndmask_b32_e64 v176, v36, v52, s[8:9]
	v_cndmask_b32_e64 v177, v37, v53, s[8:9]
	v_cndmask_b32_e64 v178, v38, v54, s[8:9]
	v_cndmask_b32_e64 v179, v39, v55, s[8:9]
	v_cndmask_b32_e64 v180, v36, v8, s[4:5]
	v_cndmask_b32_e64 v181, v37, v9, s[4:5]
	v_cndmask_b32_e64 v182, v38, v10, s[4:5]
	v_cndmask_b32_e64 v183, v39, v11, s[4:5]
	v_fma_f32 v184, v110, v36, v126
	v_fma_f32 v185, v111, v37, v127
	v_fma_f32 v186, v112, v38, v128
	v_fma_f32 v187, v113, v39, v129
	v_fmac_f32_dpp v184, v176, v102 row_ror:1 row_mask:0xf bank_mask:0xf
	v_fmac_f32_dpp v185, v177, v103 row_ror:1 row_mask:0xf bank_mask:0xf
	v_fmac_f32_dpp v186, v178, v104 row_ror:1 row_mask:0xf bank_mask:0xf
	v_fmac_f32_dpp v187, v179, v105 row_ror:1 row_mask:0xf bank_mask:0xf
	v_fmac_f32_dpp v184, v180, v118 row_ror:15 row_mask:0xf bank_mask:0xf
	v_fmac_f32_dpp v185, v181, v119 row_ror:15 row_mask:0xf bank_mask:0xf
	v_fmac_f32_dpp v186, v182, v120 row_ror:15 row_mask:0xf bank_mask:0xf
	v_fmac_f32_dpp v187, v183, v121 row_ror:15 row_mask:0xf bank_mask:0xf
	v_mul_f32_e32 v176, v184, v184
	v_mul_f32_e32 v177, v185, v185
	v_mul_f32_e32 v178, v186, v186
	v_mul_f32_e32 v179, v187, v187
	v_fmaak_f32 v176, v176, v208, 0xc0135761
	v_fmaak_f32 v177, v177, v208, 0xc0135761
	v_fmaak_f32 v178, v178, v208, 0xc0135761
	v_fmaak_f32 v179, v179, v208, 0xc0135761
	v_mul_f32_e32 v176, v176, v184
	v_mul_f32_e32 v177, v177, v185
	v_mul_f32_e32 v178, v178, v186
	v_mul_f32_e32 v179, v179, v187
	v_exp_f32_e32 v176, v176
	v_exp_f32_e32 v177, v177
	v_exp_f32_e32 v178, v178
	v_exp_f32_e32 v179, v179
	v_add_f32_e32 v176, 1.0, v176
	v_add_f32_e32 v177, 1.0, v177
	v_add_f32_e32 v178, 1.0, v178
	v_add_f32_e32 v179, 1.0, v179
	v_rcp_f32_e32 v176, v176
	v_rcp_f32_e32 v177, v177
	v_rcp_f32_e32 v178, v178
	v_rcp_f32_e32 v179, v179
	v_mul_f32_e32 v184, v184, v176
	v_mul_f32_e32 v185, v185, v177
	v_mul_f32_e32 v186, v186, v178
	v_mul_f32_e32 v187, v187, v179
	v_mul_f32_e32 v184, v184, v48
	v_mul_f32_e32 v185, v185, v49
	v_mul_f32_e32 v186, v186, v50
	v_mul_f32_e32 v187, v187, v51
	v_cvt_pk_bf16_f32 v188, v184, v185
	v_cvt_pk_bf16_f32 v189, v186, v187
	v_cndmask_b32_e64 v176, v32, v44, s[8:9]
	v_cndmask_b32_e64 v177, v33, v45, s[8:9]
	v_cndmask_b32_e64 v178, v34, v46, s[8:9]
	v_cndmask_b32_e64 v179, v35, v47, s[8:9]
	v_cndmask_b32_e64 v180, v32, v0, s[4:5]
	v_cndmask_b32_e64 v181, v33, v1, s[4:5]
	v_cndmask_b32_e64 v182, v34, v2, s[4:5]
	v_cndmask_b32_e64 v183, v35, v3, s[4:5]
	v_fma_f32 v184, v114, v32, v80
	v_fma_f32 v185, v115, v33, v81
	v_fma_f32 v186, v116, v34, v82
	v_fma_f32 v187, v117, v35, v83
	v_fmac_f32_dpp v184, v176, v106 row_ror:1 row_mask:0xf bank_mask:0xf
	v_fmac_f32_dpp v185, v177, v107 row_ror:1 row_mask:0xf bank_mask:0xf
	v_fmac_f32_dpp v186, v178, v108 row_ror:1 row_mask:0xf bank_mask:0xf
	v_fmac_f32_dpp v187, v179, v109 row_ror:1 row_mask:0xf bank_mask:0xf
	v_fmac_f32_dpp v184, v180, v122 row_ror:15 row_mask:0xf bank_mask:0xf
	v_fmac_f32_dpp v185, v181, v123 row_ror:15 row_mask:0xf bank_mask:0xf
	v_fmac_f32_dpp v186, v182, v124 row_ror:15 row_mask:0xf bank_mask:0xf
	v_fmac_f32_dpp v187, v183, v125 row_ror:15 row_mask:0xf bank_mask:0xf
	v_mul_f32_e32 v176, v184, v184
	v_mul_f32_e32 v177, v185, v185
	v_mul_f32_e32 v178, v186, v186
	v_mul_f32_e32 v179, v187, v187
	v_fmaak_f32 v176, v176, v208, 0xc0135761
	v_fmaak_f32 v177, v177, v208, 0xc0135761
	v_fmaak_f32 v178, v178, v208, 0xc0135761
	v_fmaak_f32 v179, v179, v208, 0xc0135761
	v_mul_f32_e32 v176, v176, v184
	v_mul_f32_e32 v177, v177, v185
	v_mul_f32_e32 v178, v178, v186
	v_mul_f32_e32 v179, v179, v187
	v_exp_f32_e32 v176, v176
	v_exp_f32_e32 v177, v177
	v_exp_f32_e32 v178, v178
	v_exp_f32_e32 v179, v179
	v_add_f32_e32 v176, 1.0, v176
	v_add_f32_e32 v177, 1.0, v177
	v_add_f32_e32 v178, 1.0, v178
	v_add_f32_e32 v179, 1.0, v179
	v_rcp_f32_e32 v176, v176
	v_rcp_f32_e32 v177, v177
	v_rcp_f32_e32 v178, v178
	v_rcp_f32_e32 v179, v179
	v_mul_f32_e32 v184, v184, v176
	v_mul_f32_e32 v185, v185, v177
	v_mul_f32_e32 v186, v186, v178
	v_mul_f32_e32 v187, v187, v179
	v_mul_f32_e32 v184, v184, v40
	v_mul_f32_e32 v185, v185, v41
	v_mul_f32_e32 v186, v186, v42
	v_mul_f32_e32 v187, v187, v43
	v_cvt_pk_bf16_f32 v190, v184, v185
	v_cvt_pk_bf16_f32 v191, v186, v187
	v_or_b32_e32 v176, 0xa0, v174
	v_mad_u32_u24 v176, v176, s44, v175
	global_store_dwordx4 v176, v[188:191], s[54:55]
	v_cndmask_b32_e64 v176, v8, v36, s[8:9]
	v_cndmask_b32_e64 v177, v9, v37, s[8:9]
	v_cndmask_b32_e64 v178, v10, v38, s[8:9]
	v_cndmask_b32_e64 v179, v11, v39, s[8:9]
	v_cndmask_b32_e64 v180, v8, 0, s[4:5]
	v_cndmask_b32_e64 v181, v9, 0, s[4:5]
	v_cndmask_b32_e64 v182, v10, 0, s[4:5]
	v_cndmask_b32_e64 v183, v11, 0, s[4:5]
	v_fma_f32 v184, v110, v8, v126
	v_fma_f32 v185, v111, v9, v127
	v_fma_f32 v186, v112, v10, v128
	v_fma_f32 v187, v113, v11, v129
	v_fmac_f32_dpp v184, v176, v102 row_ror:1 row_mask:0xf bank_mask:0xf
	v_fmac_f32_dpp v185, v177, v103 row_ror:1 row_mask:0xf bank_mask:0xf
	v_fmac_f32_dpp v186, v178, v104 row_ror:1 row_mask:0xf bank_mask:0xf
	v_fmac_f32_dpp v187, v179, v105 row_ror:1 row_mask:0xf bank_mask:0xf
	v_fmac_f32_dpp v184, v180, v118 row_ror:15 row_mask:0xf bank_mask:0xf
	v_fmac_f32_dpp v185, v181, v119 row_ror:15 row_mask:0xf bank_mask:0xf
	v_fmac_f32_dpp v186, v182, v120 row_ror:15 row_mask:0xf bank_mask:0xf
	v_fmac_f32_dpp v187, v183, v121 row_ror:15 row_mask:0xf bank_mask:0xf
	v_mul_f32_e32 v176, v184, v184
	v_mul_f32_e32 v177, v185, v185
	v_mul_f32_e32 v178, v186, v186
	v_mul_f32_e32 v179, v187, v187
	v_fmaak_f32 v176, v176, v208, 0xc0135761
	v_fmaak_f32 v177, v177, v208, 0xc0135761
	v_fmaak_f32 v178, v178, v208, 0xc0135761
	v_fmaak_f32 v179, v179, v208, 0xc0135761
	v_mul_f32_e32 v176, v176, v184
	v_mul_f32_e32 v177, v177, v185
	v_mul_f32_e32 v178, v178, v186
	v_mul_f32_e32 v179, v179, v187
	v_exp_f32_e32 v176, v176
	v_exp_f32_e32 v177, v177
	v_exp_f32_e32 v178, v178
	v_exp_f32_e32 v179, v179
	v_add_f32_e32 v176, 1.0, v176
	v_add_f32_e32 v177, 1.0, v177
	v_add_f32_e32 v178, 1.0, v178
	v_add_f32_e32 v179, 1.0, v179
	v_rcp_f32_e32 v176, v176
	v_rcp_f32_e32 v177, v177
	v_rcp_f32_e32 v178, v178
	v_rcp_f32_e32 v179, v179
	v_mul_f32_e32 v184, v184, v176
	v_mul_f32_e32 v185, v185, v177
	v_mul_f32_e32 v186, v186, v178
	v_mul_f32_e32 v187, v187, v179
	v_mul_f32_e32 v184, v184, v12
	v_mul_f32_e32 v185, v185, v13
	v_mul_f32_e32 v186, v186, v14
	v_mul_f32_e32 v187, v187, v15
	v_cvt_pk_bf16_f32 v188, v184, v185
	v_cvt_pk_bf16_f32 v189, v186, v187
	v_cndmask_b32_e64 v176, v0, v32, s[8:9]
	v_cndmask_b32_e64 v177, v1, v33, s[8:9]
	v_cndmask_b32_e64 v178, v2, v34, s[8:9]
	v_cndmask_b32_e64 v179, v3, v35, s[8:9]
	v_cndmask_b32_e64 v180, v0, 0, s[4:5]
	v_cndmask_b32_e64 v181, v1, 0, s[4:5]
	v_cndmask_b32_e64 v182, v2, 0, s[4:5]
	v_cndmask_b32_e64 v183, v3, 0, s[4:5]
	v_fma_f32 v184, v114, v0, v80
	v_fma_f32 v185, v115, v1, v81
	v_fma_f32 v186, v116, v2, v82
	v_fma_f32 v187, v117, v3, v83
	v_fmac_f32_dpp v184, v176, v106 row_ror:1 row_mask:0xf bank_mask:0xf
	v_fmac_f32_dpp v185, v177, v107 row_ror:1 row_mask:0xf bank_mask:0xf
	v_fmac_f32_dpp v186, v178, v108 row_ror:1 row_mask:0xf bank_mask:0xf
	v_fmac_f32_dpp v187, v179, v109 row_ror:1 row_mask:0xf bank_mask:0xf
	v_fmac_f32_dpp v184, v180, v122 row_ror:15 row_mask:0xf bank_mask:0xf
	v_fmac_f32_dpp v185, v181, v123 row_ror:15 row_mask:0xf bank_mask:0xf
	v_fmac_f32_dpp v186, v182, v124 row_ror:15 row_mask:0xf bank_mask:0xf
	v_fmac_f32_dpp v187, v183, v125 row_ror:15 row_mask:0xf bank_mask:0xf
	v_mul_f32_e32 v176, v184, v184
	v_mul_f32_e32 v177, v185, v185
	v_mul_f32_e32 v178, v186, v186
	v_mul_f32_e32 v179, v187, v187
	v_fmaak_f32 v176, v176, v208, 0xc0135761
	v_fmaak_f32 v177, v177, v208, 0xc0135761
	v_fmaak_f32 v178, v178, v208, 0xc0135761
	v_fmaak_f32 v179, v179, v208, 0xc0135761
	v_mul_f32_e32 v176, v176, v184
	v_mul_f32_e32 v177, v177, v185
	v_mul_f32_e32 v178, v178, v186
	v_mul_f32_e32 v179, v179, v187
	v_exp_f32_e32 v176, v176
	v_exp_f32_e32 v177, v177
	v_exp_f32_e32 v178, v178
	v_exp_f32_e32 v179, v179
	v_add_f32_e32 v176, 1.0, v176
	v_add_f32_e32 v177, 1.0, v177
	v_add_f32_e32 v178, 1.0, v178
	v_add_f32_e32 v179, 1.0, v179
	v_rcp_f32_e32 v176, v176
	v_rcp_f32_e32 v177, v177
	v_rcp_f32_e32 v178, v178
	v_rcp_f32_e32 v179, v179
	v_mul_f32_e32 v184, v184, v176
	v_mul_f32_e32 v185, v185, v177
	v_mul_f32_e32 v186, v186, v178
	v_mul_f32_e32 v187, v187, v179
	v_mul_f32_e32 v184, v184, v4
	v_mul_f32_e32 v185, v185, v5
	v_mul_f32_e32 v186, v186, v6
	v_mul_f32_e32 v187, v187, v7
	v_cvt_pk_bf16_f32 v190, v184, v185
	v_cvt_pk_bf16_f32 v191, v186, v187
	v_or_b32_e32 v176, 0xb0, v174
	v_mad_u32_u24 v176, v176, s44, v175
	s_and_saveexec_b64 s[38:39], s[10:11]
	global_store_dwordx4 v176, v[188:191], s[54:55]
	s_or_b64 exec, exec, s[38:39]
